# stack4: + dropped s_nop 0 after inline-asm v_max3 blocks in attention, + dead address arithmetic removed from the up-proj epilogue
# speedup vs baseline: 1.0033x; 1.0033x over previous
; template <int CTRL> DI float dppf(float v) { return __int_as_float(__builtin_amdgcn_mov_dpp(__float_as_int(v), CTRL, 0xf, 0xf, true)); }
; DI bf16* a_row(unsigned char* ws, int row) {
;     const int gb = row >> 12, s = row & 4095;
;     return (bf16*)(s < 2816 ? ws + WS_PROJ + ((size_t)gb << 24) + (size_t)s * (DFF * 2) : ws + WS_MIX + ((size_t)gb << 23) + (size_t)(s - 2816) * (DFF * 2));
;     DI void operator()(pg8::f32x4 (&acc)[2][2][4][2], const pg8::Unit& u, int wr, int wc, int fr, int fq) const {
;     ...
;                 for (int m = 0; m < 4; ++m) {
;                     float cv[2][4];
; #pragma unroll
;                     for (int bj = 0; bj < 2; ++bj) {
;                         const pg8::f32x4 cur = acc[ai][bj][m][n];
;                         pg8::f32x4 prv;
;                         if (m > 0) prv = acc[ai][bj][m > 0 ? m - 1 : 0][n]; else prv = (pg8::f32x4){hal[bj][0], hal[bj][1], hal[bj][2], hal[bj][3]};
; #pragma unroll
;                         for (int i = 0; i < 4; ++i) {
;                             const float q1 = dppf<0x121>(prv[i]), q2 = dppf<0x122>(prv[i]);
;                             const float p1 = __int_as_float(__builtin_amdgcn_update_dpp(__float_as_int(q1), __float_as_int(cur[i]), 0x111, 0xf, 0xf, false));
;                             const float p2 = __int_as_float(__builtin_amdgcn_update_dpp(__float_as_int(q2), __float_as_int(cur[i]), 0x112, 0xf, 0xf, false));
.LBB0_257:
	s_ashr_i32 s28, s34, 12
	s_ashr_i32 s29, s28, 31
	s_and_b32 s23, s34, 0xfc0
	s_lshl_b64 s[24:25], s[28:29], 23
	s_cmpk_gt_u32 s23, 0xaff
	s_waitcnt lgkmcnt(0)
	v_mov_b32_dpp v212, v166 row_ror:1 row_mask:0xf bank_mask:0xf bound_ctrl:1
	v_mov_b32_dpp v214, v166 row_ror:2 row_mask:0xf bank_mask:0xf bound_ctrl:1
	v_mov_b32_dpp v213, v167 row_ror:1 row_mask:0xf bank_mask:0xf bound_ctrl:1
	v_mov_b32_dpp v215, v167 row_ror:2 row_mask:0xf bank_mask:0xf bound_ctrl:1
	v_mov_b32_dpp v204, v168 row_ror:1 row_mask:0xf bank_mask:0xf bound_ctrl:1
	v_mov_b32_dpp v206, v168 row_ror:2 row_mask:0xf bank_mask:0xf bound_ctrl:1
	v_mov_b32_dpp v205, v169 row_ror:1 row_mask:0xf bank_mask:0xf bound_ctrl:1
	v_mov_b32_dpp v207, v169 row_ror:2 row_mask:0xf bank_mask:0xf bound_ctrl:1
	v_mov_b32_dpp v208, v162 row_ror:1 row_mask:0xf bank_mask:0xf bound_ctrl:1
	v_mov_b32_dpp v210, v162 row_ror:2 row_mask:0xf bank_mask:0xf bound_ctrl:1
	v_mov_b32_dpp v209, v163 row_ror:1 row_mask:0xf bank_mask:0xf bound_ctrl:1
	v_mov_b32_dpp v211, v163 row_ror:2 row_mask:0xf bank_mask:0xf bound_ctrl:1
	v_mov_b32_dpp v166, v164 row_ror:1 row_mask:0xf bank_mask:0xf bound_ctrl:1
	v_mov_b32_dpp v164, v164 row_ror:2 row_mask:0xf bank_mask:0xf bound_ctrl:1
	v_mov_b32_dpp v167, v165 row_ror:1 row_mask:0xf bank_mask:0xf bound_ctrl:1
	v_mov_b32_dpp v165, v165 row_ror:2 row_mask:0xf bank_mask:0xf bound_ctrl:1
	v_or_b32_e32 v201, s23, v170
	s_cselect_b64 s[26:27], -1, 0
	v_mov_b32_dpp v212, v158 row_shr:1 row_mask:0xf bank_mask:0xf
	v_mov_b32_dpp v214, v158 row_shr:2 row_mask:0xf bank_mask:0xf
	v_mov_b32_dpp v213, v159 row_shr:1 row_mask:0xf bank_mask:0xf
	v_mov_b32_dpp v215, v159 row_shr:2 row_mask:0xf bank_mask:0xf
	v_mov_b32_dpp v204, v160 row_shr:1 row_mask:0xf bank_mask:0xf
	v_mov_b32_dpp v206, v160 row_shr:2 row_mask:0xf bank_mask:0xf
	v_mov_b32_dpp v205, v161 row_shr:1 row_mask:0xf bank_mask:0xf
	v_mov_b32_dpp v207, v161 row_shr:2 row_mask:0xf bank_mask:0xf
	v_mov_b32_dpp v208, v154 row_shr:1 row_mask:0xf bank_mask:0xf
	v_mov_b32_dpp v210, v154 row_shr:2 row_mask:0xf bank_mask:0xf
	v_mov_b32_dpp v209, v155 row_shr:1 row_mask:0xf bank_mask:0xf
	v_mov_b32_dpp v211, v155 row_shr:2 row_mask:0xf bank_mask:0xf
	v_mov_b32_dpp v166, v156 row_shr:1 row_mask:0xf bank_mask:0xf
	v_mov_b32_dpp v164, v156 row_shr:2 row_mask:0xf bank_mask:0xf
	v_mov_b32_dpp v167, v157 row_shr:1 row_mask:0xf bank_mask:0xf
	v_mov_b32_dpp v165, v157 row_shr:2 row_mask:0xf bank_mask:0xf
	s_mov_b64 s[30:31], -1
	s_and_b64 vcc, exec, s[26:27]
	v_add_u32_e32 v195, 0xfffff500, v201
	s_cbranch_vccz .LBB0_259
	s_add_u32 s30, s55, s24
	s_addc_u32 s31, s58, s25
	s_mov_b64 s[30:31], 0

; DI unsigned pk2(float lo, float hi) { f32x2_t v = {lo, hi}; bf16x2_t b = __builtin_convertvector(v, bf16x2_t); return __builtin_bit_cast(unsigned, b); }
;     DI void operator()(pg8::f32x4 (&acc)[2][2][4][2], const pg8::Unit& u, int wr, int wc, int fr, int fq) const {
;     ...
;                             cv[bj][i] = cb[bj][i] + w0[bj][i] * p2 + w1[bj][i] * p1 + w2[bj][i] * cur[i];
;                         }
;                     }
;                     float o[4];
; #pragma unroll
;                     for (int i = 0; i < 4; ++i) o[i] = gelu_tanh(cv[0][i]) * cv[1][i];
;                     const int row = u.pm * 256 + ai * 128 + wr * 64 + m * 16 + fr;
;                     v2u w; w.x = pk2(o[0], o[1]); w.y = pk2(o[2], o[3]);
;                     *(v2u*)(a_row(wsb, row) + u.pn * 128 + wc * 32 + 8 * fq + 4 * n) = w;
.LBB0_261:
	s_waitcnt vmcnt(1)
	v_pk_fma_f32 v[172:173], v[122:123], v[214:215], v[134:135]
	v_pk_fma_f32 v[206:207], v[124:125], v[206:207], v[136:137]
	v_pk_fma_f32 v[172:173], v[126:127], v[212:213], v[172:173]
	v_pk_fma_f32 v[204:205], v[128:129], v[204:205], v[206:207]
	v_pk_fma_f32 v[172:173], v[158:159], v[130:131], v[172:173]
	v_pk_fma_f32 v[204:205], v[160:161], v[132:133], v[204:205]
	v_pk_mul_f32 v[212:213], v[172:173], v[172:173]
	v_pk_mul_f32 v[206:207], v[204:205], v[204:205]
	v_fmamk_f32 v64, v212, 0xbdd2d3e7, v175
	v_mul_f32_e32 v64, v172, v64
	v_fmamk_f32 v163, v213, 0xbdd2d3e7, v175
	v_exp_f32_e32 v64, v64
	v_mul_f32_e32 v163, v173, v163
	v_exp_f32_e32 v163, v163
	s_waitcnt vmcnt(0)
	v_pk_fma_f32 v[164:165], v[104:105], v[164:165], v[120:121]
	v_add_f32_e32 v64, 1.0, v64
	v_rcp_f32_e32 v212, v64
	v_add_f32_e32 v64, 1.0, v163
	v_rcp_f32_e32 v213, v64
	v_fmamk_f32 v64, v206, 0xbdd2d3e7, v175
	v_mul_f32_e32 v64, v204, v64
	v_fmamk_f32 v163, v207, 0xbdd2d3e7, v175
	v_exp_f32_e32 v64, v64
	v_mul_f32_e32 v163, v205, v163
	v_exp_f32_e32 v163, v163
	v_pk_fma_f32 v[164:165], v[108:109], v[166:167], v[164:165]
	v_add_f32_e32 v64, 1.0, v64
	v_rcp_f32_e32 v206, v64
	v_add_f32_e32 v64, 1.0, v163
	v_rcp_f32_e32 v207, v64
	v_pk_fma_f32 v[210:211], v[102:103], v[210:211], v[118:119]
	v_pk_fma_f32 v[164:165], v[156:157], v[116:117], v[164:165]
	s_lshl_b32 s22, s22, 7
	v_pk_mul_f32 v[166:167], v[204:205], v[206:207]
	v_pk_fma_f32 v[208:209], v[106:107], v[208:209], v[210:211]
	v_pk_mul_f32 v[164:165], v[166:167], v[164:165]
	s_ashr_i32 s23, s22, 31
	v_pk_fma_f32 v[208:209], v[154:155], v[114:115], v[208:209]
	v_pk_mul_f32 v[172:173], v[172:173], v[212:213]
	v_cvt_pk_bf16_f32 v221, v164, v165
	v_pk_mul_f32 v[164:165], v[142:143], v[200:201] op_sel_hi:[1,0]
	v_pk_mul_f32 v[142:143], v[138:139], v[200:201] op_sel_hi:[1,0]
	s_lshl_b32 s72, s6, 1
	v_pk_mul_f32 v[172:173], v[172:173], v[208:209]
	v_lshlrev_b32_e32 v64, 1, v184
	v_cvt_pk_bf16_f32 v220, v172, v173
	v_pk_mul_f32 v[144:145], v[144:145], v[200:201] op_sel_hi:[1,0]
	v_pk_mul_f32 v[140:141], v[140:141], v[200:201] op_sel_hi:[1,0]
	v_mov_b32_dpp v206, v158 row_ror:1 row_mask:0xf bank_mask:0xf bound_ctrl:1
	v_mov_b32_dpp v208, v158 row_ror:2 row_mask:0xf bank_mask:0xf bound_ctrl:1
	v_mov_b32_dpp v207, v159 row_ror:1 row_mask:0xf bank_mask:0xf bound_ctrl:1
	v_mov_b32_dpp v209, v159 row_ror:2 row_mask:0xf bank_mask:0xf bound_ctrl:1
	v_mov_b32_dpp v158, v160 row_ror:1 row_mask:0xf bank_mask:0xf bound_ctrl:1
	v_mov_b32_dpp v160, v160 row_ror:2 row_mask:0xf bank_mask:0xf bound_ctrl:1
	v_mov_b32_dpp v159, v161 row_ror:1 row_mask:0xf bank_mask:0xf bound_ctrl:1
	v_mov_b32_dpp v161, v161 row_ror:2 row_mask:0xf bank_mask:0xf bound_ctrl:1
	v_mov_b32_dpp v168, v154 row_ror:1 row_mask:0xf bank_mask:0xf bound_ctrl:1
	v_mov_b32_dpp v204, v154 row_ror:2 row_mask:0xf bank_mask:0xf bound_ctrl:1
	v_mov_b32_dpp v169, v155 row_ror:1 row_mask:0xf bank_mask:0xf bound_ctrl:1
	v_mov_b32_dpp v205, v155 row_ror:2 row_mask:0xf bank_mask:0xf bound_ctrl:1
	v_mov_b32_dpp v154, v156 row_ror:1 row_mask:0xf bank_mask:0xf bound_ctrl:1
	v_mov_b32_dpp v156, v156 row_ror:2 row_mask:0xf bank_mask:0xf bound_ctrl:1
	v_mov_b32_dpp v155, v157 row_ror:1 row_mask:0xf bank_mask:0xf bound_ctrl:1
	v_mov_b32_dpp v157, v157 row_ror:2 row_mask:0xf bank_mask:0xf bound_ctrl:1
	v_cndmask_b32_e64 v138, 0, 1, s[26:27]
	v_mov_b32_dpp v206, v164 row_shr:1 row_mask:0xf bank_mask:0xf
	v_mov_b32_dpp v208, v164 row_shr:2 row_mask:0xf bank_mask:0xf
	v_mov_b32_dpp v207, v165 row_shr:1 row_mask:0xf bank_mask:0xf
	v_mov_b32_dpp v209, v165 row_shr:2 row_mask:0xf bank_mask:0xf
	v_mov_b32_dpp v158, v144 row_shr:1 row_mask:0xf bank_mask:0xf
	v_mov_b32_dpp v160, v144 row_shr:2 row_mask:0xf bank_mask:0xf
	v_mov_b32_dpp v159, v145 row_shr:1 row_mask:0xf bank_mask:0xf
	v_mov_b32_dpp v161, v145 row_shr:2 row_mask:0xf bank_mask:0xf
	v_mov_b32_dpp v168, v142 row_shr:1 row_mask:0xf bank_mask:0xf
	v_mov_b32_dpp v204, v142 row_shr:2 row_mask:0xf bank_mask:0xf
	v_mov_b32_dpp v169, v143 row_shr:1 row_mask:0xf bank_mask:0xf
	v_mov_b32_dpp v205, v143 row_shr:2 row_mask:0xf bank_mask:0xf
	v_mov_b32_dpp v154, v140 row_shr:1 row_mask:0xf bank_mask:0xf
	v_mov_b32_dpp v156, v140 row_shr:2 row_mask:0xf bank_mask:0xf
	v_mov_b32_dpp v155, v141 row_shr:1 row_mask:0xf bank_mask:0xf
	v_mov_b32_dpp v157, v141 row_shr:2 row_mask:0xf bank_mask:0xf
	s_mov_b64 s[30:31], -1
	v_cmp_ne_u32_e64 s[44:45], 1, v138
	s_andn2_b64 vcc, exec, s[26:27]
	v_add_u32_e32 v199, 0xfffff510, v201
	s_cbranch_vccnz .LBB0_263
	s_add_u32 s26, s55, s24
	s_addc_u32 s27, s58, s25
	s_mov_b64 s[30:31], 0

; DI unsigned pk2(float lo, float hi) { f32x2_t v = {lo, hi}; bf16x2_t b = __builtin_convertvector(v, bf16x2_t); return __builtin_bit_cast(unsigned, b); }
;     DI void operator()(pg8::f32x4 (&acc)[2][2][4][2], const pg8::Unit& u, int wr, int wc, int fr, int fq) const {
;     ...
;                             cv[bj][i] = cb[bj][i] + w0[bj][i] * p2 + w1[bj][i] * p1 + w2[bj][i] * cur[i];
;                         }
;                     }
;                     float o[4];
; #pragma unroll
;                     for (int i = 0; i < 4; ++i) o[i] = gelu_tanh(cv[0][i]) * cv[1][i];
;                     const int row = u.pm * 256 + ai * 128 + wr * 64 + m * 16 + fr;
;                     v2u w; w.x = pk2(o[0], o[1]); w.y = pk2(o[2], o[3]);
;                     *(v2u*)(a_row(wsb, row) + u.pn * 128 + wc * 32 + 8 * fq + 4 * n) = w;
.LBB0_265:
	v_pk_fma_f32 v[172:173], v[122:123], v[208:209], v[134:135]
	v_pk_fma_f32 v[160:161], v[124:125], v[160:161], v[136:137]
	v_pk_fma_f32 v[172:173], v[126:127], v[206:207], v[172:173]
	v_pk_fma_f32 v[158:159], v[128:129], v[158:159], v[160:161]
	v_pk_fma_f32 v[172:173], v[164:165], v[130:131], v[172:173]
	v_pk_fma_f32 v[158:159], v[144:145], v[132:133], v[158:159]
	v_pk_mul_f32 v[206:207], v[172:173], v[172:173]
	v_pk_mul_f32 v[160:161], v[158:159], v[158:159]
	v_fmamk_f32 v139, v206, 0xbdd2d3e7, v175
	v_mul_f32_e32 v139, v172, v139
	v_fmamk_f32 v163, v207, 0xbdd2d3e7, v175
	v_exp_f32_e32 v139, v139
	v_mul_f32_e32 v163, v173, v163
	v_exp_f32_e32 v163, v163
	v_pk_fma_f32 v[204:205], v[102:103], v[204:205], v[118:119]
	v_add_f32_e32 v139, 1.0, v139
	v_rcp_f32_e32 v206, v139
	v_add_f32_e32 v139, 1.0, v163
	v_rcp_f32_e32 v207, v139
	v_fmamk_f32 v139, v160, 0xbdd2d3e7, v175
	v_mul_f32_e32 v139, v158, v139
	v_fmamk_f32 v160, v161, 0xbdd2d3e7, v175
	v_exp_f32_e32 v139, v139
	v_mul_f32_e32 v160, v159, v160
	v_exp_f32_e32 v163, v160
	v_pk_fma_f32 v[168:169], v[106:107], v[168:169], v[204:205]
	v_pk_mul_f32 v[172:173], v[172:173], v[206:207]
	v_pk_fma_f32 v[168:169], v[142:143], v[114:115], v[168:169]
	v_add_f32_e32 v139, 1.0, v139
	v_pk_mul_f32 v[160:161], v[172:173], v[168:169]
	v_rcp_f32_e32 v168, v139
	v_add_f32_e32 v139, 1.0, v163
	v_rcp_f32_e32 v169, v139
	v_pk_fma_f32 v[156:157], v[104:105], v[156:157], v[120:121]
	v_pk_mul_f32 v[112:113], v[112:113], v[198:199] op_sel_hi:[1,0]
	v_pk_fma_f32 v[154:155], v[108:109], v[154:155], v[156:157]
	v_pk_mul_f32 v[156:157], v[158:159], v[168:169]
	v_pk_fma_f32 v[154:155], v[140:141], v[116:117], v[154:155]
	v_pk_mul_f32 v[100:101], v[100:101], v[198:199] op_sel_hi:[1,0]
	v_pk_mul_f32 v[154:155], v[156:157], v[154:155]
	v_cvt_pk_bf16_f32 v222, v160, v161
	v_cvt_pk_bf16_f32 v223, v154, v155
	v_pk_mul_f32 v[154:155], v[110:111], v[198:199] op_sel_hi:[1,0]
	v_pk_mul_f32 v[98:99], v[98:99], v[198:199] op_sel_hi:[1,0]
	v_mov_b32_dpp v166, v164 row_ror:1 row_mask:0xf bank_mask:0xf bound_ctrl:1
	v_mov_b32_dpp v168, v164 row_ror:2 row_mask:0xf bank_mask:0xf bound_ctrl:1
	v_mov_b32_dpp v167, v165 row_ror:1 row_mask:0xf bank_mask:0xf bound_ctrl:1
	v_mov_b32_dpp v169, v165 row_ror:2 row_mask:0xf bank_mask:0xf bound_ctrl:1
	v_mov_b32_dpp v156, v144 row_ror:1 row_mask:0xf bank_mask:0xf bound_ctrl:1
	v_mov_b32_dpp v144, v144 row_ror:2 row_mask:0xf bank_mask:0xf bound_ctrl:1
	v_mov_b32_dpp v157, v145 row_ror:1 row_mask:0xf bank_mask:0xf bound_ctrl:1
	v_mov_b32_dpp v145, v145 row_ror:2 row_mask:0xf bank_mask:0xf bound_ctrl:1
	v_mov_b32_dpp v160, v142 row_ror:1 row_mask:0xf bank_mask:0xf bound_ctrl:1
	v_mov_b32_dpp v164, v142 row_ror:2 row_mask:0xf bank_mask:0xf bound_ctrl:1
	v_mov_b32_dpp v161, v143 row_ror:1 row_mask:0xf bank_mask:0xf bound_ctrl:1
	v_mov_b32_dpp v165, v143 row_ror:2 row_mask:0xf bank_mask:0xf bound_ctrl:1
	v_mov_b32_dpp v142, v140 row_ror:1 row_mask:0xf bank_mask:0xf bound_ctrl:1
	v_mov_b32_dpp v140, v140 row_ror:2 row_mask:0xf bank_mask:0xf bound_ctrl:1
	v_mov_b32_dpp v143, v141 row_ror:1 row_mask:0xf bank_mask:0xf bound_ctrl:1
	v_mov_b32_dpp v141, v141 row_ror:2 row_mask:0xf bank_mask:0xf bound_ctrl:1
	v_mov_b32_dpp v166, v154 row_shr:1 row_mask:0xf bank_mask:0xf
	v_mov_b32_dpp v168, v154 row_shr:2 row_mask:0xf bank_mask:0xf
	v_mov_b32_dpp v167, v155 row_shr:1 row_mask:0xf bank_mask:0xf
	v_mov_b32_dpp v169, v155 row_shr:2 row_mask:0xf bank_mask:0xf
	v_mov_b32_dpp v156, v112 row_shr:1 row_mask:0xf bank_mask:0xf
	v_mov_b32_dpp v144, v112 row_shr:2 row_mask:0xf bank_mask:0xf
	v_mov_b32_dpp v157, v113 row_shr:1 row_mask:0xf bank_mask:0xf
	v_mov_b32_dpp v145, v113 row_shr:2 row_mask:0xf bank_mask:0xf
	v_mov_b32_dpp v160, v98 row_shr:1 row_mask:0xf bank_mask:0xf
	v_mov_b32_dpp v164, v98 row_shr:2 row_mask:0xf bank_mask:0xf
	v_mov_b32_dpp v161, v99 row_shr:1 row_mask:0xf bank_mask:0xf
	v_mov_b32_dpp v165, v99 row_shr:2 row_mask:0xf bank_mask:0xf
	v_mov_b32_dpp v142, v100 row_shr:1 row_mask:0xf bank_mask:0xf
	v_mov_b32_dpp v140, v100 row_shr:2 row_mask:0xf bank_mask:0xf
	v_mov_b32_dpp v143, v101 row_shr:1 row_mask:0xf bank_mask:0xf
	v_mov_b32_dpp v141, v101 row_shr:2 row_mask:0xf bank_mask:0xf
	s_mov_b64 s[26:27], -1
	s_and_b64 vcc, exec, s[44:45]
	v_add_u32_e32 v197, 0xfffff520, v201
	s_cbranch_vccnz .LBB0_267
	s_add_u32 s26, s55, s24
	s_addc_u32 s27, s58, s25
	s_mov_b64 s[26:27], 0

; DI unsigned pk2(float lo, float hi) { f32x2_t v = {lo, hi}; bf16x2_t b = __builtin_convertvector(v, bf16x2_t); return __builtin_bit_cast(unsigned, b); }
;     DI void operator()(pg8::f32x4 (&acc)[2][2][4][2], const pg8::Unit& u, int wr, int wc, int fr, int fq) const {
;     ...
;                             cv[bj][i] = cb[bj][i] + w0[bj][i] * p2 + w1[bj][i] * p1 + w2[bj][i] * cur[i];
;                         }
;                     }
;                     float o[4];
; #pragma unroll
;                     for (int i = 0; i < 4; ++i) o[i] = gelu_tanh(cv[0][i]) * cv[1][i];
;                     const int row = u.pm * 256 + ai * 128 + wr * 64 + m * 16 + fr;
;                     v2u w; w.x = pk2(o[0], o[1]); w.y = pk2(o[2], o[3]);
;                     *(v2u*)(a_row(wsb, row) + u.pn * 128 + wc * 32 + 8 * fq + 4 * n) = w;
.LBB0_269:
	v_pk_fma_f32 v[168:169], v[122:123], v[168:169], v[134:135]
	v_pk_fma_f32 v[144:145], v[124:125], v[144:145], v[136:137]
	v_pk_fma_f32 v[166:167], v[126:127], v[166:167], v[168:169]
	v_pk_fma_f32 v[144:145], v[128:129], v[156:157], v[144:145]
	v_pk_fma_f32 v[166:167], v[154:155], v[130:131], v[166:167]
	v_pk_fma_f32 v[144:145], v[112:113], v[132:133], v[144:145]
	v_pk_mul_f32 v[168:169], v[166:167], v[166:167]
	v_pk_mul_f32 v[156:157], v[144:145], v[144:145]
	v_fmamk_f32 v111, v168, 0xbdd2d3e7, v175
	v_mul_f32_e32 v111, v166, v111
	v_fmamk_f32 v139, v169, 0xbdd2d3e7, v175
	v_exp_f32_e32 v111, v111
	v_mul_f32_e32 v139, v167, v139
	v_exp_f32_e32 v139, v139
	v_pk_fma_f32 v[164:165], v[102:103], v[164:165], v[118:119]
	v_add_f32_e32 v111, 1.0, v111
	v_rcp_f32_e32 v168, v111
	v_add_f32_e32 v111, 1.0, v139
	v_rcp_f32_e32 v169, v111
	v_fmamk_f32 v111, v156, 0xbdd2d3e7, v175
	v_mul_f32_e32 v111, v144, v111
	v_fmamk_f32 v139, v157, 0xbdd2d3e7, v175
	v_exp_f32_e32 v111, v111
	v_mul_f32_e32 v139, v145, v139
	v_exp_f32_e32 v139, v139
	v_pk_fma_f32 v[160:161], v[106:107], v[160:161], v[164:165]
	v_pk_mul_f32 v[164:165], v[166:167], v[168:169]
	v_pk_fma_f32 v[160:161], v[98:99], v[114:115], v[160:161]
	v_add_f32_e32 v111, 1.0, v111
	v_pk_mul_f32 v[156:157], v[164:165], v[160:161]
	v_rcp_f32_e32 v160, v111
	v_add_f32_e32 v111, 1.0, v139
	v_rcp_f32_e32 v161, v111
	v_pk_fma_f32 v[140:141], v[104:105], v[140:141], v[120:121]
	s_mov_b64 s[26:27], -1
	v_pk_fma_f32 v[140:141], v[108:109], v[142:143], v[140:141]
	v_pk_mul_f32 v[142:143], v[144:145], v[160:161]
	v_pk_fma_f32 v[140:141], v[100:101], v[116:117], v[140:141]
	v_mov_b32_dpp v160, v154 row_ror:2 row_mask:0xf bank_mask:0xf bound_ctrl:1
	v_pk_mul_f32 v[140:141], v[142:143], v[140:141]
	v_cvt_pk_bf16_f32 v224, v156, v157
	v_cvt_pk_bf16_f32 v225, v140, v141
	v_mov_b32_dpp v158, v154 row_ror:1 row_mask:0xf bank_mask:0xf bound_ctrl:1
	v_mov_b32_dpp v159, v155 row_ror:1 row_mask:0xf bank_mask:0xf bound_ctrl:1
	v_mov_b32_dpp v161, v155 row_ror:2 row_mask:0xf bank_mask:0xf bound_ctrl:1
	v_mov_b32_dpp v140, v112 row_ror:1 row_mask:0xf bank_mask:0xf bound_ctrl:1
	v_mov_b32_dpp v142, v112 row_ror:2 row_mask:0xf bank_mask:0xf bound_ctrl:1
	v_mov_b32_dpp v141, v113 row_ror:1 row_mask:0xf bank_mask:0xf bound_ctrl:1
	v_mov_b32_dpp v143, v113 row_ror:2 row_mask:0xf bank_mask:0xf bound_ctrl:1
	v_mov_b32_dpp v154, v98 row_ror:1 row_mask:0xf bank_mask:0xf bound_ctrl:1
	v_mov_b32_dpp v156, v98 row_ror:2 row_mask:0xf bank_mask:0xf bound_ctrl:1
	v_mov_b32_dpp v155, v99 row_ror:1 row_mask:0xf bank_mask:0xf bound_ctrl:1
	v_mov_b32_dpp v157, v99 row_ror:2 row_mask:0xf bank_mask:0xf bound_ctrl:1
	v_mov_b32_dpp v98, v100 row_ror:1 row_mask:0xf bank_mask:0xf bound_ctrl:1
	v_mov_b32_dpp v100, v100 row_ror:2 row_mask:0xf bank_mask:0xf bound_ctrl:1
	v_mov_b32_dpp v99, v101 row_ror:1 row_mask:0xf bank_mask:0xf bound_ctrl:1
	v_mov_b32_dpp v101, v101 row_ror:2 row_mask:0xf bank_mask:0xf bound_ctrl:1
	v_mov_b32_dpp v158, v150 row_shr:1 row_mask:0xf bank_mask:0xf
	v_mov_b32_dpp v160, v150 row_shr:2 row_mask:0xf bank_mask:0xf
	v_mov_b32_dpp v159, v151 row_shr:1 row_mask:0xf bank_mask:0xf
	v_mov_b32_dpp v161, v151 row_shr:2 row_mask:0xf bank_mask:0xf
	v_mov_b32_dpp v140, v152 row_shr:1 row_mask:0xf bank_mask:0xf
	v_mov_b32_dpp v142, v152 row_shr:2 row_mask:0xf bank_mask:0xf
	v_mov_b32_dpp v141, v153 row_shr:1 row_mask:0xf bank_mask:0xf
	v_mov_b32_dpp v143, v153 row_shr:2 row_mask:0xf bank_mask:0xf
	v_mov_b32_dpp v154, v146 row_shr:1 row_mask:0xf bank_mask:0xf
	v_mov_b32_dpp v156, v146 row_shr:2 row_mask:0xf bank_mask:0xf
	v_mov_b32_dpp v155, v147 row_shr:1 row_mask:0xf bank_mask:0xf
	v_mov_b32_dpp v157, v147 row_shr:2 row_mask:0xf bank_mask:0xf
	v_mov_b32_dpp v98, v148 row_shr:1 row_mask:0xf bank_mask:0xf
	v_mov_b32_dpp v100, v148 row_shr:2 row_mask:0xf bank_mask:0xf
	v_mov_b32_dpp v99, v149 row_shr:1 row_mask:0xf bank_mask:0xf
	v_mov_b32_dpp v101, v149 row_shr:2 row_mask:0xf bank_mask:0xf
	s_and_b64 vcc, exec, s[44:45]
	v_add_u32_e32 v164, 0xfffff530, v201
	s_cbranch_vccnz .LBB0_271
	s_add_u32 s26, s55, s24
	s_addc_u32 s27, s58, s25
	s_mov_b64 s[26:27], 0

; DI unsigned pk2(float lo, float hi) { f32x2_t v = {lo, hi}; bf16x2_t b = __builtin_convertvector(v, bf16x2_t); return __builtin_bit_cast(unsigned, b); }
; template <int CTRL> DI float dppf(float v) { return __int_as_float(__builtin_amdgcn_mov_dpp(__float_as_int(v), CTRL, 0xf, 0xf, true)); }
;     DI void operator()(pg8::f32x4 (&acc)[2][2][4][2], const pg8::Unit& u, int wr, int wc, int fr, int fq) const {
;     ...
;             for (int ai = 0; ai < 2; ++ai) {
;                 v4f hal[2];
;                 {
;                     const bool has = (wr == 1) || (ai == 1);
;                     const int as = (wr == 1) ? ai : 0, ws_ = (wr == 1) ? 0 : 1;
; #pragma unroll
;                     for (int bj = 0; bj < 2; ++bj) { v4f hv = H[(((as * 2 + ws_) * 4 + wc) * 4 + bj * 2 + n) * 8 + hl]; hal[bj] = has ? hv : (v4f){0.f, 0.f, 0.f, 0.f}; }
;                 }
; #pragma unroll
;                 for (int m = 0; m < 4; ++m) {
;                     float cv[2][4];
; #pragma unroll
;                     for (int bj = 0; bj < 2; ++bj) {
;                         const pg8::f32x4 cur = acc[ai][bj][m][n];
;                         pg8::f32x4 prv;
;                         if (m > 0) prv = acc[ai][bj][m > 0 ? m - 1 : 0][n]; else prv = (pg8::f32x4){hal[bj][0], hal[bj][1], hal[bj][2], hal[bj][3]};
; #pragma unroll
;                         for (int i = 0; i < 4; ++i) {
;                             const float q1 = dppf<0x121>(prv[i]), q2 = dppf<0x122>(prv[i]);
;                             const float p1 = __int_as_float(__builtin_amdgcn_update_dpp(__float_as_int(q1), __float_as_int(cur[i]), 0x111, 0xf, 0xf, false));
;                             const float p2 = __int_as_float(__builtin_amdgcn_update_dpp(__float_as_int(q2), __float_as_int(cur[i]), 0x112, 0xf, 0xf, false));
;                             cv[bj][i] = cb[bj][i] + w0[bj][i] * p2 + w1[bj][i] * p1 + w2[bj][i] * cur[i];
;                         }
;                     }
;                     float o[4];
; #pragma unroll
;                     for (int i = 0; i < 4; ++i) o[i] = gelu_tanh(cv[0][i]) * cv[1][i];
;                     const int row = u.pm * 256 + ai * 128 + wr * 64 + m * 16 + fr;
;                     v2u w; w.x = pk2(o[0], o[1]); w.y = pk2(o[2], o[3]);
;                     *(v2u*)(a_row(wsb, row) + u.pn * 128 + wc * 32 + 8 * fq + 4 * n) = w;
.LBB0_273:
	v_pk_fma_f32 v[160:161], v[122:123], v[160:161], v[134:135]
	v_pk_fma_f32 v[142:143], v[124:125], v[142:143], v[136:137]
	v_pk_fma_f32 v[158:159], v[126:127], v[158:159], v[160:161]
	v_pk_fma_f32 v[140:141], v[128:129], v[140:141], v[142:143]
	v_pk_fma_f32 v[150:151], v[150:151], v[130:131], v[158:159]
	v_pk_fma_f32 v[140:141], v[152:153], v[132:133], v[140:141]
	v_pk_mul_f32 v[158:159], v[150:151], v[150:151]
	v_pk_mul_f32 v[142:143], v[140:141], v[140:141]
	v_fmamk_f32 v111, v158, 0xbdd2d3e7, v175
	v_mul_f32_e32 v111, v150, v111
	v_fmamk_f32 v113, v159, 0xbdd2d3e7, v175
	v_exp_f32_e32 v111, v111
	v_mul_f32_e32 v113, v151, v113
	v_exp_f32_e32 v113, v113
	v_pk_fma_f32 v[156:157], v[102:103], v[156:157], v[118:119]
	v_add_f32_e32 v111, 1.0, v111
	v_rcp_f32_e32 v158, v111
	v_add_f32_e32 v111, 1.0, v113
	v_rcp_f32_e32 v159, v111
	v_fmamk_f32 v111, v142, 0xbdd2d3e7, v175
	v_mul_f32_e32 v111, v140, v111
	v_fmamk_f32 v113, v143, 0xbdd2d3e7, v175
	v_exp_f32_e32 v111, v111
	v_mul_f32_e32 v113, v141, v113
	v_exp_f32_e32 v113, v113
	v_pk_fma_f32 v[154:155], v[106:107], v[154:155], v[156:157]
	v_pk_mul_f32 v[150:151], v[150:151], v[158:159]
	v_pk_fma_f32 v[146:147], v[146:147], v[114:115], v[154:155]
	v_add_f32_e32 v111, 1.0, v111
	v_pk_mul_f32 v[142:143], v[150:151], v[146:147]
	v_rcp_f32_e32 v146, v111
	v_add_f32_e32 v111, 1.0, v113
	v_rcp_f32_e32 v147, v111
	v_pk_fma_f32 v[100:101], v[104:105], v[100:101], v[120:121]
	s_addk_i32 s34, 0x80
	v_pk_fma_f32 v[98:99], v[108:109], v[98:99], v[100:101]
	v_pk_mul_f32 v[100:101], v[140:141], v[146:147]
	v_pk_fma_f32 v[98:99], v[148:149], v[116:117], v[98:99]
	s_ashr_i32 s30, s34, 12
	v_pk_mul_f32 v[98:99], v[100:101], v[98:99]
	v_cvt_pk_bf16_f32 v232, v142, v143
	v_cvt_pk_bf16_f32 v233, v98, v99
	ds_read_b128 v[140:143], v218
	ds_read_b128 v[144:147], v218 offset:256
	s_ashr_i32 s31, s30, 31
	s_and_b32 s49, s34, 0xfc0
	s_lshl_b64 s[26:27], s[30:31], 23
	v_pk_mul_f32 v[84:85], v[84:85], v[196:197] op_sel_hi:[1,0]
	v_pk_mul_f32 v[82:83], v[82:83], v[196:197] op_sel_hi:[1,0]
	v_pk_mul_f32 v[76:77], v[76:77], v[196:197] op_sel_hi:[1,0]
	v_pk_mul_f32 v[74:75], v[74:75], v[196:197] op_sel_hi:[1,0]
	s_waitcnt lgkmcnt(1)
	v_mov_b32_dpp v152, v140 row_ror:1 row_mask:0xf bank_mask:0xf bound_ctrl:1
	v_mov_b32_dpp v154, v140 row_ror:2 row_mask:0xf bank_mask:0xf bound_ctrl:1
	v_mov_b32_dpp v153, v141 row_ror:1 row_mask:0xf bank_mask:0xf bound_ctrl:1
	v_mov_b32_dpp v155, v141 row_ror:2 row_mask:0xf bank_mask:0xf bound_ctrl:1
	v_mov_b32_dpp v100, v142 row_ror:1 row_mask:0xf bank_mask:0xf bound_ctrl:1
	v_mov_b32_dpp v142, v142 row_ror:2 row_mask:0xf bank_mask:0xf bound_ctrl:1
	v_mov_b32_dpp v101, v143 row_ror:1 row_mask:0xf bank_mask:0xf bound_ctrl:1
	v_mov_b32_dpp v143, v143 row_ror:2 row_mask:0xf bank_mask:0xf bound_ctrl:1
	s_waitcnt lgkmcnt(0)
	v_mov_b32_dpp v148, v144 row_ror:1 row_mask:0xf bank_mask:0xf bound_ctrl:1
	v_mov_b32_dpp v150, v144 row_ror:2 row_mask:0xf bank_mask:0xf bound_ctrl:1
	v_mov_b32_dpp v149, v145 row_ror:1 row_mask:0xf bank_mask:0xf bound_ctrl:1
	v_mov_b32_dpp v151, v145 row_ror:2 row_mask:0xf bank_mask:0xf bound_ctrl:1
	v_mov_b32_dpp v98, v146 row_ror:1 row_mask:0xf bank_mask:0xf bound_ctrl:1
	v_mov_b32_dpp v140, v146 row_ror:2 row_mask:0xf bank_mask:0xf bound_ctrl:1
	v_mov_b32_dpp v99, v147 row_ror:1 row_mask:0xf bank_mask:0xf bound_ctrl:1
	v_mov_b32_dpp v141, v147 row_ror:2 row_mask:0xf bank_mask:0xf bound_ctrl:1
	v_or_b32_e32 v111, s49, v170
	s_cmpk_gt_u32 s49, 0xaff
	v_mov_b32_dpp v152, v82 row_shr:1 row_mask:0xf bank_mask:0xf
	v_mov_b32_dpp v154, v82 row_shr:2 row_mask:0xf bank_mask:0xf
	v_mov_b32_dpp v153, v83 row_shr:1 row_mask:0xf bank_mask:0xf
	v_mov_b32_dpp v155, v83 row_shr:2 row_mask:0xf bank_mask:0xf
	v_mov_b32_dpp v100, v84 row_shr:1 row_mask:0xf bank_mask:0xf
	v_mov_b32_dpp v142, v84 row_shr:2 row_mask:0xf bank_mask:0xf
	v_mov_b32_dpp v101, v85 row_shr:1 row_mask:0xf bank_mask:0xf
	v_mov_b32_dpp v143, v85 row_shr:2 row_mask:0xf bank_mask:0xf
	v_mov_b32_dpp v148, v74 row_shr:1 row_mask:0xf bank_mask:0xf
	v_mov_b32_dpp v150, v74 row_shr:2 row_mask:0xf bank_mask:0xf
	v_mov_b32_dpp v149, v75 row_shr:1 row_mask:0xf bank_mask:0xf
	v_mov_b32_dpp v151, v75 row_shr:2 row_mask:0xf bank_mask:0xf
	v_mov_b32_dpp v98, v76 row_shr:1 row_mask:0xf bank_mask:0xf
	v_mov_b32_dpp v140, v76 row_shr:2 row_mask:0xf bank_mask:0xf
	v_mov_b32_dpp v99, v77 row_shr:1 row_mask:0xf bank_mask:0xf
	v_mov_b32_dpp v141, v77 row_shr:2 row_mask:0xf bank_mask:0xf
	s_mov_b64 s[46:47], -1
	s_cselect_b64 s[34:35], -1, 0
	s_cmpk_lt_u32 s49, 0xb00
	v_add_u32_e32 v156, 0xfffff500, v111
	s_cbranch_scc1 .LBB0_275
	s_add_u32 s46, s55, s26
	s_addc_u32 s47, s58, s27
	v_mov_b64_e32 v[144:145], s[46:47]
	v_mad_u64_u32 v[144:145], s[46:47], v156, s0, v[144:145]
	s_mov_b64 s[46:47], 0

; DI unsigned pk2(float lo, float hi) { f32x2_t v = {lo, hi}; bf16x2_t b = __builtin_convertvector(v, bf16x2_t); return __builtin_bit_cast(unsigned, b); }
;     DI void operator()(pg8::f32x4 (&acc)[2][2][4][2], const pg8::Unit& u, int wr, int wc, int fr, int fq) const {
;     ...
;                             cv[bj][i] = cb[bj][i] + w0[bj][i] * p2 + w1[bj][i] * p1 + w2[bj][i] * cur[i];
;                         }
;                     }
;                     float o[4];
; #pragma unroll
;                     for (int i = 0; i < 4; ++i) o[i] = gelu_tanh(cv[0][i]) * cv[1][i];
;                     const int row = u.pm * 256 + ai * 128 + wr * 64 + m * 16 + fr;
;                     v2u w; w.x = pk2(o[0], o[1]); w.y = pk2(o[2], o[3]);
;                     *(v2u*)(a_row(wsb, row) + u.pn * 128 + wc * 32 + 8 * fq + 4 * n) = w;
.LBB0_277:
	v_pk_fma_f32 v[154:155], v[122:123], v[154:155], v[134:135]
	v_pk_fma_f32 v[142:143], v[124:125], v[142:143], v[136:137]
	v_pk_fma_f32 v[152:153], v[126:127], v[152:153], v[154:155]
	v_pk_fma_f32 v[100:101], v[128:129], v[100:101], v[142:143]
	v_pk_fma_f32 v[152:153], v[82:83], v[130:131], v[152:153]
	v_pk_fma_f32 v[100:101], v[84:85], v[132:133], v[100:101]
	v_pk_mul_f32 v[154:155], v[152:153], v[152:153]
	v_pk_mul_f32 v[142:143], v[100:101], v[100:101]
	v_fmamk_f32 v113, v154, 0xbdd2d3e7, v175
	v_mul_f32_e32 v113, v152, v113
	v_fmamk_f32 v139, v155, 0xbdd2d3e7, v175
	v_exp_f32_e32 v113, v113
	v_mul_f32_e32 v139, v153, v139
	v_exp_f32_e32 v139, v139
	v_pk_fma_f32 v[150:151], v[102:103], v[150:151], v[118:119]
	v_add_f32_e32 v113, 1.0, v113
	v_rcp_f32_e32 v154, v113
	v_add_f32_e32 v113, 1.0, v139
	v_rcp_f32_e32 v155, v113
	v_fmamk_f32 v113, v142, 0xbdd2d3e7, v175
	v_mul_f32_e32 v113, v100, v113
	v_fmamk_f32 v139, v143, 0xbdd2d3e7, v175
	v_exp_f32_e32 v113, v113
	v_mul_f32_e32 v139, v101, v139
	v_exp_f32_e32 v139, v139
	v_pk_fma_f32 v[148:149], v[106:107], v[148:149], v[150:151]
	v_pk_mul_f32 v[150:151], v[152:153], v[154:155]
	v_pk_fma_f32 v[148:149], v[74:75], v[114:115], v[148:149]
	v_add_f32_e32 v113, 1.0, v113
	v_pk_mul_f32 v[142:143], v[150:151], v[148:149]
	v_rcp_f32_e32 v148, v113
	v_add_f32_e32 v113, 1.0, v139
	v_rcp_f32_e32 v149, v113
	v_pk_fma_f32 v[140:141], v[104:105], v[140:141], v[120:121]
	v_pk_mul_f32 v[72:73], v[72:73], v[194:195] op_sel_hi:[1,0]
	v_pk_fma_f32 v[98:99], v[108:109], v[98:99], v[140:141]
	v_pk_mul_f32 v[100:101], v[100:101], v[148:149]
	v_pk_fma_f32 v[98:99], v[76:77], v[116:117], v[98:99]
	v_pk_mul_f32 v[70:71], v[70:71], v[194:195] op_sel_hi:[1,0]
	v_pk_mul_f32 v[98:99], v[100:101], v[98:99]
	v_cvt_pk_bf16_f32 v238, v142, v143
	v_cvt_pk_bf16_f32 v239, v98, v99
	v_pk_mul_f32 v[68:69], v[68:69], v[194:195] op_sel_hi:[1,0]
	v_pk_mul_f32 v[66:67], v[66:67], v[194:195] op_sel_hi:[1,0]
	v_mov_b32_dpp v142, v82 row_ror:1 row_mask:0xf bank_mask:0xf bound_ctrl:1
	v_mov_b32_dpp v148, v82 row_ror:2 row_mask:0xf bank_mask:0xf bound_ctrl:1
	v_mov_b32_dpp v143, v83 row_ror:1 row_mask:0xf bank_mask:0xf bound_ctrl:1
	v_mov_b32_dpp v149, v83 row_ror:2 row_mask:0xf bank_mask:0xf bound_ctrl:1
	v_mov_b32_dpp v82, v84 row_ror:1 row_mask:0xf bank_mask:0xf bound_ctrl:1
	v_mov_b32_dpp v84, v84 row_ror:2 row_mask:0xf bank_mask:0xf bound_ctrl:1
	v_mov_b32_dpp v83, v85 row_ror:1 row_mask:0xf bank_mask:0xf bound_ctrl:1
	v_mov_b32_dpp v85, v85 row_ror:2 row_mask:0xf bank_mask:0xf bound_ctrl:1
	v_mov_b32_dpp v100, v74 row_ror:1 row_mask:0xf bank_mask:0xf bound_ctrl:1
	v_mov_b32_dpp v140, v74 row_ror:2 row_mask:0xf bank_mask:0xf bound_ctrl:1
	v_mov_b32_dpp v101, v75 row_ror:1 row_mask:0xf bank_mask:0xf bound_ctrl:1
	v_mov_b32_dpp v141, v75 row_ror:2 row_mask:0xf bank_mask:0xf bound_ctrl:1
	v_mov_b32_dpp v74, v76 row_ror:1 row_mask:0xf bank_mask:0xf bound_ctrl:1
	v_mov_b32_dpp v76, v76 row_ror:2 row_mask:0xf bank_mask:0xf bound_ctrl:1
	v_mov_b32_dpp v75, v77 row_ror:1 row_mask:0xf bank_mask:0xf bound_ctrl:1
	v_mov_b32_dpp v77, v77 row_ror:2 row_mask:0xf bank_mask:0xf bound_ctrl:1
	v_cndmask_b32_e64 v98, 0, 1, s[34:35]
	v_mov_b32_dpp v142, v70 row_shr:1 row_mask:0xf bank_mask:0xf
	v_mov_b32_dpp v148, v70 row_shr:2 row_mask:0xf bank_mask:0xf
	v_mov_b32_dpp v143, v71 row_shr:1 row_mask:0xf bank_mask:0xf
	v_mov_b32_dpp v149, v71 row_shr:2 row_mask:0xf bank_mask:0xf
	v_mov_b32_dpp v82, v72 row_shr:1 row_mask:0xf bank_mask:0xf
	v_mov_b32_dpp v84, v72 row_shr:2 row_mask:0xf bank_mask:0xf
	v_mov_b32_dpp v83, v73 row_shr:1 row_mask:0xf bank_mask:0xf
	v_mov_b32_dpp v85, v73 row_shr:2 row_mask:0xf bank_mask:0xf
	v_mov_b32_dpp v100, v66 row_shr:1 row_mask:0xf bank_mask:0xf
	v_mov_b32_dpp v140, v66 row_shr:2 row_mask:0xf bank_mask:0xf
	v_mov_b32_dpp v101, v67 row_shr:1 row_mask:0xf bank_mask:0xf
	v_mov_b32_dpp v141, v67 row_shr:2 row_mask:0xf bank_mask:0xf
	v_mov_b32_dpp v74, v68 row_shr:1 row_mask:0xf bank_mask:0xf
	v_mov_b32_dpp v76, v68 row_shr:2 row_mask:0xf bank_mask:0xf
	v_mov_b32_dpp v75, v69 row_shr:1 row_mask:0xf bank_mask:0xf
	v_mov_b32_dpp v77, v69 row_shr:2 row_mask:0xf bank_mask:0xf
	s_mov_b64 s[74:75], -1
	v_cmp_ne_u32_e64 s[46:47], 1, v98
	s_andn2_b64 vcc, exec, s[34:35]
	v_add_u32_e32 v150, 0xfffff510, v111
	s_cbranch_vccnz .LBB0_279
	s_add_u32 s34, s55, s26
	s_addc_u32 s35, s58, s27
	s_mov_b64 s[74:75], 0

; DI unsigned pk2(float lo, float hi) { f32x2_t v = {lo, hi}; bf16x2_t b = __builtin_convertvector(v, bf16x2_t); return __builtin_bit_cast(unsigned, b); }
;     DI void operator()(pg8::f32x4 (&acc)[2][2][4][2], const pg8::Unit& u, int wr, int wc, int fr, int fq) const {
;     ...
;                             cv[bj][i] = cb[bj][i] + w0[bj][i] * p2 + w1[bj][i] * p1 + w2[bj][i] * cur[i];
;                         }
;                     }
;                     float o[4];
; #pragma unroll
;                     for (int i = 0; i < 4; ++i) o[i] = gelu_tanh(cv[0][i]) * cv[1][i];
;                     const int row = u.pm * 256 + ai * 128 + wr * 64 + m * 16 + fr;
;                     v2u w; w.x = pk2(o[0], o[1]); w.y = pk2(o[2], o[3]);
;                     *(v2u*)(a_row(wsb, row) + u.pn * 128 + wc * 32 + 8 * fq + 4 * n) = w;
.LBB0_281:
	v_pk_fma_f32 v[148:149], v[122:123], v[148:149], v[134:135]
	v_pk_fma_f32 v[84:85], v[124:125], v[84:85], v[136:137]
	v_pk_fma_f32 v[142:143], v[126:127], v[142:143], v[148:149]
	v_pk_fma_f32 v[82:83], v[128:129], v[82:83], v[84:85]
	v_pk_fma_f32 v[142:143], v[70:71], v[130:131], v[142:143]
	v_pk_fma_f32 v[82:83], v[72:73], v[132:133], v[82:83]
	v_pk_mul_f32 v[148:149], v[142:143], v[142:143]
	v_pk_mul_f32 v[84:85], v[82:83], v[82:83]
	v_fmamk_f32 v113, v148, 0xbdd2d3e7, v175
	v_mul_f32_e32 v113, v142, v113
	v_fmamk_f32 v139, v149, 0xbdd2d3e7, v175
	v_exp_f32_e32 v113, v113
	v_mul_f32_e32 v139, v143, v139
	v_exp_f32_e32 v139, v139
	v_fmamk_f32 v84, v84, 0xbdd2d3e7, v175
	v_add_f32_e32 v113, 1.0, v113
	v_rcp_f32_e32 v148, v113
	v_add_f32_e32 v113, 1.0, v139
	v_mul_f32_e32 v84, v82, v84
	v_rcp_f32_e32 v149, v113
	v_exp_f32_e32 v113, v84
	v_fmamk_f32 v84, v85, 0xbdd2d3e7, v175
	v_mul_f32_e32 v84, v83, v84
	v_exp_f32_e32 v139, v84
	v_pk_fma_f32 v[140:141], v[102:103], v[140:141], v[118:119]
	v_pk_fma_f32 v[76:77], v[104:105], v[76:77], v[120:121]
	v_pk_fma_f32 v[100:101], v[106:107], v[100:101], v[140:141]
	v_pk_mul_f32 v[140:141], v[142:143], v[148:149]
	v_pk_fma_f32 v[100:101], v[66:67], v[114:115], v[100:101]
	v_pk_fma_f32 v[74:75], v[108:109], v[74:75], v[76:77]
	v_pk_mul_f32 v[84:85], v[140:141], v[100:101]
	v_add_f32_e32 v100, 1.0, v113
	v_add_f32_e32 v101, 1.0, v139
	v_rcp_f32_e32 v100, v100
	v_rcp_f32_e32 v101, v101
	v_pk_fma_f32 v[74:75], v[68:69], v[116:117], v[74:75]
	v_pk_mul_f32 v[62:63], v[62:63], v[192:193] op_sel_hi:[1,0]
	v_pk_mul_f32 v[60:61], v[60:61], v[192:193] op_sel_hi:[1,0]
	v_pk_mul_f32 v[76:77], v[82:83], v[100:101]
	v_pk_mul_f32 v[58:59], v[58:59], v[192:193] op_sel_hi:[1,0]
	v_pk_mul_f32 v[74:75], v[76:77], v[74:75]
	v_cvt_pk_bf16_f32 v242, v84, v85
	v_cvt_pk_bf16_f32 v243, v74, v75
	v_pk_mul_f32 v[56:57], v[56:57], v[192:193] op_sel_hi:[1,0]
	v_mov_b32_dpp v84, v70 row_ror:1 row_mask:0xf bank_mask:0xf bound_ctrl:1
	v_mov_b32_dpp v98, v70 row_ror:2 row_mask:0xf bank_mask:0xf bound_ctrl:1
	v_mov_b32_dpp v85, v71 row_ror:1 row_mask:0xf bank_mask:0xf bound_ctrl:1
	v_mov_b32_dpp v99, v71 row_ror:2 row_mask:0xf bank_mask:0xf bound_ctrl:1
	v_mov_b32_dpp v70, v72 row_ror:1 row_mask:0xf bank_mask:0xf bound_ctrl:1
	v_mov_b32_dpp v72, v72 row_ror:2 row_mask:0xf bank_mask:0xf bound_ctrl:1
	v_mov_b32_dpp v71, v73 row_ror:1 row_mask:0xf bank_mask:0xf bound_ctrl:1
	v_mov_b32_dpp v73, v73 row_ror:2 row_mask:0xf bank_mask:0xf bound_ctrl:1
	v_mov_b32_dpp v76, v66 row_ror:1 row_mask:0xf bank_mask:0xf bound_ctrl:1
	v_mov_b32_dpp v82, v66 row_ror:2 row_mask:0xf bank_mask:0xf bound_ctrl:1
	v_mov_b32_dpp v77, v67 row_ror:1 row_mask:0xf bank_mask:0xf bound_ctrl:1
	v_mov_b32_dpp v83, v67 row_ror:2 row_mask:0xf bank_mask:0xf bound_ctrl:1
	v_mov_b32_dpp v66, v68 row_ror:1 row_mask:0xf bank_mask:0xf bound_ctrl:1
	v_mov_b32_dpp v68, v68 row_ror:2 row_mask:0xf bank_mask:0xf bound_ctrl:1
	v_mov_b32_dpp v67, v69 row_ror:1 row_mask:0xf bank_mask:0xf bound_ctrl:1
	v_mov_b32_dpp v69, v69 row_ror:2 row_mask:0xf bank_mask:0xf bound_ctrl:1
	v_mov_b32_dpp v84, v60 row_shr:1 row_mask:0xf bank_mask:0xf
	v_mov_b32_dpp v98, v60 row_shr:2 row_mask:0xf bank_mask:0xf
	v_mov_b32_dpp v85, v61 row_shr:1 row_mask:0xf bank_mask:0xf
	v_mov_b32_dpp v99, v61 row_shr:2 row_mask:0xf bank_mask:0xf
	v_mov_b32_dpp v70, v62 row_shr:1 row_mask:0xf bank_mask:0xf
	v_mov_b32_dpp v72, v62 row_shr:2 row_mask:0xf bank_mask:0xf
	v_mov_b32_dpp v71, v63 row_shr:1 row_mask:0xf bank_mask:0xf
	v_mov_b32_dpp v73, v63 row_shr:2 row_mask:0xf bank_mask:0xf
	v_mov_b32_dpp v76, v56 row_shr:1 row_mask:0xf bank_mask:0xf
	v_mov_b32_dpp v82, v56 row_shr:2 row_mask:0xf bank_mask:0xf
	v_mov_b32_dpp v77, v57 row_shr:1 row_mask:0xf bank_mask:0xf
	v_mov_b32_dpp v83, v57 row_shr:2 row_mask:0xf bank_mask:0xf
	v_mov_b32_dpp v66, v58 row_shr:1 row_mask:0xf bank_mask:0xf
	v_mov_b32_dpp v68, v58 row_shr:2 row_mask:0xf bank_mask:0xf
	v_mov_b32_dpp v67, v59 row_shr:1 row_mask:0xf bank_mask:0xf
	v_mov_b32_dpp v69, v59 row_shr:2 row_mask:0xf bank_mask:0xf
	s_mov_b64 s[34:35], -1
	s_and_b64 vcc, exec, s[46:47]
	v_add_u32_e32 v148, 0xfffff520, v111
	s_cbranch_vccnz .LBB0_283
	s_add_u32 s34, s55, s26
	s_addc_u32 s35, s58, s27
	s_mov_b64 s[34:35], 0

; DI unsigned pk2(float lo, float hi) { f32x2_t v = {lo, hi}; bf16x2_t b = __builtin_convertvector(v, bf16x2_t); return __builtin_bit_cast(unsigned, b); }
;     DI void operator()(pg8::f32x4 (&acc)[2][2][4][2], const pg8::Unit& u, int wr, int wc, int fr, int fq) const {
;     ...
;                             cv[bj][i] = cb[bj][i] + w0[bj][i] * p2 + w1[bj][i] * p1 + w2[bj][i] * cur[i];
;                         }
;                     }
;                     float o[4];
; #pragma unroll
;                     for (int i = 0; i < 4; ++i) o[i] = gelu_tanh(cv[0][i]) * cv[1][i];
;                     const int row = u.pm * 256 + ai * 128 + wr * 64 + m * 16 + fr;
;                     v2u w; w.x = pk2(o[0], o[1]); w.y = pk2(o[2], o[3]);
;                     *(v2u*)(a_row(wsb, row) + u.pn * 128 + wc * 32 + 8 * fq + 4 * n) = w;
.LBB0_285:
	v_pk_fma_f32 v[98:99], v[122:123], v[98:99], v[134:135]
	v_pk_fma_f32 v[72:73], v[124:125], v[72:73], v[136:137]
	v_pk_fma_f32 v[84:85], v[126:127], v[84:85], v[98:99]
	v_pk_fma_f32 v[70:71], v[128:129], v[70:71], v[72:73]
	v_pk_fma_f32 v[84:85], v[60:61], v[130:131], v[84:85]
	v_pk_fma_f32 v[70:71], v[62:63], v[132:133], v[70:71]
	v_pk_mul_f32 v[98:99], v[84:85], v[84:85]
	v_pk_mul_f32 v[72:73], v[70:71], v[70:71]
	v_fmamk_f32 v98, v98, 0xbdd2d3e7, v175
	v_fmamk_f32 v99, v99, 0xbdd2d3e7, v175
	v_mul_f32_e32 v98, v84, v98
	v_mul_f32_e32 v99, v85, v99
	v_exp_f32_e32 v98, v98
	v_exp_f32_e32 v99, v99
	v_fmamk_f32 v72, v72, 0xbdd2d3e7, v175
	v_pk_fma_f32 v[82:83], v[102:103], v[82:83], v[118:119]
	v_add_f32_e32 v98, 1.0, v98
	v_add_f32_e32 v99, 1.0, v99
	v_rcp_f32_e32 v98, v98
	v_rcp_f32_e32 v99, v99
	v_mul_f32_e32 v72, v70, v72
	v_pk_fma_f32 v[76:77], v[106:107], v[76:77], v[82:83]
	v_pk_fma_f32 v[68:69], v[104:105], v[68:69], v[120:121]
	v_pk_mul_f32 v[82:83], v[84:85], v[98:99]
	v_exp_f32_e32 v84, v72
	v_fmamk_f32 v72, v73, 0xbdd2d3e7, v175
	v_mul_f32_e32 v72, v71, v72
	v_exp_f32_e32 v85, v72
	v_pk_fma_f32 v[76:77], v[56:57], v[114:115], v[76:77]
	v_pk_fma_f32 v[66:67], v[108:109], v[66:67], v[68:69]
	v_pk_mul_f32 v[72:73], v[82:83], v[76:77]
	v_add_f32_e32 v76, 1.0, v84
	v_add_f32_e32 v77, 1.0, v85
	v_rcp_f32_e32 v76, v76
	v_rcp_f32_e32 v77, v77
	v_pk_fma_f32 v[66:67], v[58:59], v[116:117], v[66:67]
	s_mov_b64 s[34:35], -1
	s_and_b64 vcc, exec, s[46:47]
	v_pk_mul_f32 v[68:69], v[70:71], v[76:77]
	v_mov_b32_dpp v70, v56 row_ror:2 row_mask:0xf bank_mask:0xf bound_ctrl:1
	v_pk_mul_f32 v[66:67], v[68:69], v[66:67]
	v_cvt_pk_bf16_f32 v248, v72, v73
	v_cvt_pk_bf16_f32 v249, v66, v67
	v_mov_b32_dpp v72, v60 row_ror:1 row_mask:0xf bank_mask:0xf bound_ctrl:1
	v_mov_b32_dpp v74, v60 row_ror:2 row_mask:0xf bank_mask:0xf bound_ctrl:1
	v_mov_b32_dpp v73, v61 row_ror:1 row_mask:0xf bank_mask:0xf bound_ctrl:1
	v_mov_b32_dpp v75, v61 row_ror:2 row_mask:0xf bank_mask:0xf bound_ctrl:1
	v_mov_b32_dpp v60, v62 row_ror:1 row_mask:0xf bank_mask:0xf bound_ctrl:1
	v_mov_b32_dpp v62, v62 row_ror:2 row_mask:0xf bank_mask:0xf bound_ctrl:1
	v_mov_b32_dpp v61, v63 row_ror:1 row_mask:0xf bank_mask:0xf bound_ctrl:1
	v_mov_b32_dpp v63, v63 row_ror:2 row_mask:0xf bank_mask:0xf bound_ctrl:1
	v_mov_b32_dpp v68, v56 row_ror:1 row_mask:0xf bank_mask:0xf bound_ctrl:1
	v_mov_b32_dpp v69, v57 row_ror:1 row_mask:0xf bank_mask:0xf bound_ctrl:1
	v_mov_b32_dpp v71, v57 row_ror:2 row_mask:0xf bank_mask:0xf bound_ctrl:1
	v_mov_b32_dpp v56, v58 row_ror:1 row_mask:0xf bank_mask:0xf bound_ctrl:1
	v_mov_b32_dpp v58, v58 row_ror:2 row_mask:0xf bank_mask:0xf bound_ctrl:1
	v_mov_b32_dpp v57, v59 row_ror:1 row_mask:0xf bank_mask:0xf bound_ctrl:1
	v_mov_b32_dpp v59, v59 row_ror:2 row_mask:0xf bank_mask:0xf bound_ctrl:1
	v_mov_b32_dpp v72, v94 row_shr:1 row_mask:0xf bank_mask:0xf
	v_mov_b32_dpp v74, v94 row_shr:2 row_mask:0xf bank_mask:0xf
	v_mov_b32_dpp v73, v95 row_shr:1 row_mask:0xf bank_mask:0xf
	v_mov_b32_dpp v75, v95 row_shr:2 row_mask:0xf bank_mask:0xf
	v_mov_b32_dpp v60, v96 row_shr:1 row_mask:0xf bank_mask:0xf
	v_mov_b32_dpp v62, v96 row_shr:2 row_mask:0xf bank_mask:0xf
	v_mov_b32_dpp v61, v97 row_shr:1 row_mask:0xf bank_mask:0xf
	v_mov_b32_dpp v63, v97 row_shr:2 row_mask:0xf bank_mask:0xf
	v_mov_b32_dpp v68, v90 row_shr:1 row_mask:0xf bank_mask:0xf
	v_mov_b32_dpp v70, v90 row_shr:2 row_mask:0xf bank_mask:0xf
	v_mov_b32_dpp v69, v91 row_shr:1 row_mask:0xf bank_mask:0xf
	v_mov_b32_dpp v71, v91 row_shr:2 row_mask:0xf bank_mask:0xf
	v_mov_b32_dpp v56, v92 row_shr:1 row_mask:0xf bank_mask:0xf
	v_mov_b32_dpp v58, v92 row_shr:2 row_mask:0xf bank_mask:0xf
	v_mov_b32_dpp v57, v93 row_shr:1 row_mask:0xf bank_mask:0xf
	v_mov_b32_dpp v59, v93 row_shr:2 row_mask:0xf bank_mask:0xf
	v_add_u32_e32 v149, 0xfffff530, v111
	s_cbranch_vccnz .LBB0_287
	s_add_u32 s34, s55, s26
	s_addc_u32 s35, s58, s27
	s_mov_b64 s[34:35], 0

; DI unsigned pk2(float lo, float hi) { f32x2_t v = {lo, hi}; bf16x2_t b = __builtin_convertvector(v, bf16x2_t); return __builtin_bit_cast(unsigned, b); }
;     DI void operator()(pg8::f32x4 (&acc)[2][2][4][2], const pg8::Unit& u, int wr, int wc, int fr, int fq) const {
;     ...
;             v4f w0[2], w1[2], w2[2], cb[2];
; #pragma unroll
;             for (int bj = 0; bj < 2; ++bj) {
;                 const float* p = cwp + u.pn * 256 + bj * 128 + wc * 32 + 8 * fq + 4 * n;
;                 w0[bj] = *(const v4f*)p; w1[bj] = *(const v4f*)(p + NUP); w2[bj] = *(const v4f*)(p + 2 * NUP); cb[bj] = *(const v4f*)(p + 3 * NUP);
;             }
; #pragma unroll
;             for (int ai = 0; ai < 2; ++ai) {
;                 v4f hal[2];
;                 {
;                     const bool has = (wr == 1) || (ai == 1);
;                     const int as = (wr == 1) ? ai : 0, ws_ = (wr == 1) ? 0 : 1;
; #pragma unroll
;                     for (int bj = 0; bj < 2; ++bj) { v4f hv = H[(((as * 2 + ws_) * 4 + wc) * 4 + bj * 2 + n) * 8 + hl]; hal[bj] = has ? hv : (v4f){0.f, 0.f, 0.f, 0.f}; }
;     ...
;                             cv[bj][i] = cb[bj][i] + w0[bj][i] * p2 + w1[bj][i] * p1 + w2[bj][i] * cur[i];
;                         }
;                     }
;                     float o[4];
; #pragma unroll
;                     for (int i = 0; i < 4; ++i) o[i] = gelu_tanh(cv[0][i]) * cv[1][i];
;                     const int row = u.pm * 256 + ai * 128 + wr * 64 + m * 16 + fr;
;                     v2u w; w.x = pk2(o[0], o[1]); w.y = pk2(o[2], o[3]);
;                     *(v2u*)(a_row(wsb, row) + u.pn * 128 + wc * 32 + 8 * fq + 4 * n) = w;
.LBB0_289:
	v_pk_fma_f32 v[74:75], v[122:123], v[74:75], v[134:135]
	v_pk_fma_f32 v[62:63], v[124:125], v[62:63], v[136:137]
	v_pk_fma_f32 v[72:73], v[126:127], v[72:73], v[74:75]
	v_pk_fma_f32 v[60:61], v[128:129], v[60:61], v[62:63]
	v_pk_fma_f32 v[72:73], v[94:95], v[130:131], v[72:73]
	v_pk_fma_f32 v[60:61], v[96:97], v[132:133], v[60:61]
	v_pk_mul_f32 v[74:75], v[72:73], v[72:73]
	v_pk_mul_f32 v[62:63], v[60:61], v[60:61]
	v_fmamk_f32 v74, v74, 0xbdd2d3e7, v175
	v_fmamk_f32 v75, v75, 0xbdd2d3e7, v175
	v_mul_f32_e32 v74, v72, v74
	v_mul_f32_e32 v75, v73, v75
	v_exp_f32_e32 v74, v74
	v_exp_f32_e32 v75, v75
	v_fmamk_f32 v62, v62, 0xbdd2d3e7, v175
	v_pk_fma_f32 v[70:71], v[102:103], v[70:71], v[118:119]
	v_add_f32_e32 v74, 1.0, v74
	v_add_f32_e32 v75, 1.0, v75
	v_rcp_f32_e32 v74, v74
	v_rcp_f32_e32 v75, v75
	v_mul_f32_e32 v62, v60, v62
	v_pk_fma_f32 v[68:69], v[106:107], v[68:69], v[70:71]
	v_pk_fma_f32 v[58:59], v[104:105], v[58:59], v[120:121]
	v_pk_mul_f32 v[70:71], v[72:73], v[74:75]
	v_exp_f32_e32 v72, v62
	v_fmamk_f32 v62, v63, 0xbdd2d3e7, v175
	v_mul_f32_e32 v62, v61, v62
	v_exp_f32_e32 v73, v62
	v_pk_fma_f32 v[68:69], v[90:91], v[114:115], v[68:69]
	v_pk_fma_f32 v[56:57], v[108:109], v[56:57], v[58:59]
	v_pk_mul_f32 v[62:63], v[70:71], v[68:69]
	v_add_f32_e32 v68, 1.0, v72
	v_add_f32_e32 v69, 1.0, v73
	v_rcp_f32_e32 v68, v68
	v_rcp_f32_e32 v69, v69
	v_pk_fma_f32 v[56:57], v[92:93], v[116:117], v[56:57]
	v_mov_b32_e32 v98, 0
	v_mov_b32_e32 v102, 0
	v_pk_mul_f32 v[58:59], v[60:61], v[68:69]
	v_add_co_u32_e32 v60, vcc, 0x5000, v202
	v_pk_mul_f32 v[56:57], v[58:59], v[56:57]
	s_nop 0
	v_addc_co_u32_e32 v61, vcc, 0, v203, vcc
	v_cvt_pk_bf16_f32 v251, v56, v57
	v_add_co_u32_e32 v66, vcc, 0xb000, v202
	s_nop 0
	v_addc_co_u32_e32 v67, vcc, 0, v203, vcc
	v_cvt_pk_bf16_f32 v250, v62, v63
	v_add_co_u32_e32 v70, vcc, 0x10000, v202
	s_nop 0
	v_addc_co_u32_e32 v71, vcc, 0, v203, vcc
	global_load_dwordx4 v[74:77], v[202:203], off offset:16
	global_load_dwordx4 v[56:59], v[202:203], off offset:528
	global_load_dwordx4 v[82:85], v[60:61], off offset:2064
	s_nop 0
	global_load_dwordx4 v[60:63], v[60:61], off offset:2576
	s_nop 0
	global_load_dwordx4 v[90:93], v[66:67], off offset:16
	s_nop 0
	global_load_dwordx4 v[66:69], v[66:67], off offset:528
	s_nop 0
	global_load_dwordx4 v[94:97], v[70:71], off offset:2064
	s_nop 0
	global_load_dwordx4 v[70:73], v[70:71], off offset:2576
	s_and_b64 vcc, exec, s[42:43]
	v_mov_b32_e32 v103, 0
	v_mov_b32_e32 v104, 0
	v_mov_b32_e32 v105, 0
	s_cbranch_vccnz .LBB0_291
	ds_read_b128 v[102:105], v193 offset:128

; DI float max3f(float a, float b, float c) { float r; asm("v_max3_f32 %0, %1, %2, %3" : "=v"(r) : "v"(a), "v"(b), "v"(c)); return r; }
; DI float max2f(float a, float b) { float r; asm("v_max_f32_e32 %0, %1, %2" : "=v"(r) : "v"(a), "v"(b)); return r; }
; template <int MODE> DI void attn_unit(int b, int qb, const bf16* Qb, int qpitch, const bf16* Kb, int kpitch, const bf16* VT, bf16* O, float* ssq, ...
;     ...
;             { float ma = max3f(p0[0], p0[1], p1[0]), mb = max3f(p0[2], p0[3], p1[1]); ma = max3f(ma, p1[2], p1[3]);
; #pragma unroll
;               for (int r = 4; r < 16; r += 4) { ma = max3f(ma, p0[r], p0[r + 1]); mb = max3f(mb, p0[r + 2], p0[r + 3]); ma = max3f(ma, p1[r], p1[r + 1]); mb = max3f(mb, p1[r + 2], p1[r + 3]); }
;               rm = max2f(ma, mb); }
;             { const auto rr = __builtin_amdgcn_permlane32_swap(__float_as_uint(rm), __float_as_uint(rm), false, false); rm = max2f(__uint_as_float(rr[0]), __uint_as_float(rr[1])); }
;             const float mn = max2f(m, rm), corr = __builtin_amdgcn_exp2f(m - mn);
;             m = mn;
;             float rs = 0.f;
; #pragma unroll
;             for (int r = 0; r < 16; ++r) { p0[r] = __builtin_amdgcn_exp2f(p0[r] - mn); p1[r] = __builtin_amdgcn_exp2f(p1[r] - mn); rs += p0[r] + p1[r]; }
;             lsum = lsum * corr + rs;
;             if (__any(corr != 1.0f)) {
; #pragma unroll
;                 for (int r = 0; r < 16; ++r) { o0[r] *= corr; o1[r] *= corr; }
;             }
.LBB0_472:
	v_max3_f32 v153, v48, v49, v32
	v_max3_f32 v159, v50, v51, v33
	v_max3_f32 v153, v153, v34, v35
	v_max3_f32 v159, v159, v54, v55
	v_max3_f32 v153, v153, v52, v53
	v_max3_f32 v159, v159, v38, v39
	v_max3_f32 v153, v153, v36, v37
	v_max3_f32 v159, v159, v58, v59
	v_max3_f32 v153, v153, v56, v57
	v_max3_f32 v159, v159, v42, v43
	v_max3_f32 v153, v153, v40, v41
	v_max3_f32 v159, v159, v62, v63
	v_max3_f32 v153, v153, v60, v61
	v_max3_f32 v159, v159, v46, v47
	v_max3_f32 v153, v153, v44, v45
	v_max_f32_e32 v153, v153, v159
	v_mov_b32_e32 v159, v153
	s_nop 1
	v_permlane32_swap_b32_e32 v153, v159
	v_max_f32_e32 v153, v153, v159
	v_max_f32_e32 v153, v157, v153
	v_sub_f32_e32 v157, v157, v153
	v_exp_f32_e32 v190, v157
	s_nop 0
	v_cmp_neq_f32_e32 vcc, 1.0, v190
	s_cbranch_vccz .LBB0_474
	v_pk_mul_f32 v[14:15], v[14:15], v[190:191] op_sel_hi:[1,0]
	v_pk_mul_f32 v[12:13], v[12:13], v[190:191] op_sel_hi:[1,0]
	v_pk_mul_f32 v[10:11], v[10:11], v[190:191] op_sel_hi:[1,0]
	v_pk_mul_f32 v[8:9], v[8:9], v[190:191] op_sel_hi:[1,0]
	v_pk_mul_f32 v[6:7], v[6:7], v[190:191] op_sel_hi:[1,0]
	v_pk_mul_f32 v[4:5], v[4:5], v[190:191] op_sel_hi:[1,0]
	v_pk_mul_f32 v[2:3], v[2:3], v[190:191] op_sel_hi:[1,0]
	v_pk_mul_f32 v[0:1], v[0:1], v[190:191] op_sel_hi:[1,0]
	v_pk_mul_f32 v[30:31], v[30:31], v[190:191] op_sel_hi:[1,0]
	v_pk_mul_f32 v[28:29], v[28:29], v[190:191] op_sel_hi:[1,0]
	v_pk_mul_f32 v[26:27], v[26:27], v[190:191] op_sel_hi:[1,0]
	v_pk_mul_f32 v[24:25], v[24:25], v[190:191] op_sel_hi:[1,0]
	v_pk_mul_f32 v[22:23], v[22:23], v[190:191] op_sel_hi:[1,0]
	v_pk_mul_f32 v[20:21], v[20:21], v[190:191] op_sel_hi:[1,0]
	v_pk_mul_f32 v[18:19], v[18:19], v[190:191] op_sel_hi:[1,0]
	v_pk_mul_f32 v[16:17], v[16:17], v[190:191] op_sel_hi:[1,0]

; DI float max3f(float a, float b, float c) { float r; asm("v_max3_f32 %0, %1, %2, %3" : "=v"(r) : "v"(a), "v"(b), "v"(c)); return r; }
; DI float max2f(float a, float b) { float r; asm("v_max_f32_e32 %0, %1, %2" : "=v"(r) : "v"(a), "v"(b)); return r; }
; template <int MODE> DI void attn_unit(int b, int qb, const bf16* Qb, int qpitch, const bf16* Kb, int kpitch, const bf16* VT, bf16* O, float* ssq, ...
;     ...
;             { float ma = max3f(p0[0], p0[1], p1[0]), mb = max3f(p0[2], p0[3], p1[1]); ma = max3f(ma, p1[2], p1[3]);
; #pragma unroll
;               for (int r = 4; r < 16; r += 4) { ma = max3f(ma, p0[r], p0[r + 1]); mb = max3f(mb, p0[r + 2], p0[r + 3]); ma = max3f(ma, p1[r], p1[r + 1]); mb = max3f(mb, p1[r + 2], p1[r + 3]); }
;               rm = max2f(ma, mb); }
;             { const auto rr = __builtin_amdgcn_permlane32_swap(__float_as_uint(rm), __float_as_uint(rm), false, false); rm = max2f(__uint_as_float(rr[0]), __uint_as_float(rr[1])); }
;             const float mn = max2f(m, rm), corr = __builtin_amdgcn_exp2f(m - mn);
;             m = mn;
;             float rs = 0.f;
; #pragma unroll
;             for (int r = 0; r < 16; ++r) { p0[r] = __builtin_amdgcn_exp2f(p0[r] - mn); p1[r] = __builtin_amdgcn_exp2f(p1[r] - mn); rs += p0[r] + p1[r]; }
;             lsum = lsum * corr + rs;
;             if (__any(corr != 1.0f)) {
; #pragma unroll
;                 for (int r = 0; r < 16; ++r) { o0[r] *= corr; o1[r] *= corr; }
;             }
.LBB0_511:
	v_max3_f32 v42, v188, v189, v32
	v_max3_f32 v43, v186, v187, v33
	v_max3_f32 v42, v42, v34, v35
	v_max3_f32 v43, v43, v182, v183
	v_max3_f32 v42, v42, v184, v185
	v_max3_f32 v43, v43, v38, v39
	v_max3_f32 v42, v42, v58, v59
	v_max3_f32 v43, v43, v48, v49
	v_max3_f32 v42, v42, v54, v55
	v_max3_f32 v43, v43, v40, v41
	v_max3_f32 v42, v42, v56, v57
	v_max3_f32 v43, v43, v50, v51
	v_max3_f32 v42, v42, v52, v53
	v_max3_f32 v43, v43, v36, v37
	v_max3_f32 v42, v42, v44, v45
	v_max_f32_e32 v42, v42, v43
	v_mov_b32_e32 v43, v42
	s_nop 1
	v_permlane32_swap_b32_e32 v42, v43
	v_max_f32_e32 v42, v42, v43
	v_max_f32_e32 v43, v169, v42
	v_sub_f32_e32 v42, v169, v43
	v_exp_f32_e32 v42, v42
	s_nop 0
	v_cmp_neq_f32_e32 vcc, 1.0, v42
	s_cbranch_vccz .LBB0_513
	v_pk_mul_f32 v[30:31], v[30:31], v[42:43] op_sel_hi:[1,0]
	v_pk_mul_f32 v[28:29], v[28:29], v[42:43] op_sel_hi:[1,0]
	v_pk_mul_f32 v[26:27], v[26:27], v[42:43] op_sel_hi:[1,0]
	v_pk_mul_f32 v[24:25], v[24:25], v[42:43] op_sel_hi:[1,0]
	v_pk_mul_f32 v[22:23], v[22:23], v[42:43] op_sel_hi:[1,0]
	v_pk_mul_f32 v[20:21], v[20:21], v[42:43] op_sel_hi:[1,0]
	v_pk_mul_f32 v[18:19], v[18:19], v[42:43] op_sel_hi:[1,0]
	v_pk_mul_f32 v[16:17], v[16:17], v[42:43] op_sel_hi:[1,0]
	v_pk_mul_f32 v[14:15], v[14:15], v[42:43] op_sel_hi:[1,0]
	v_pk_mul_f32 v[12:13], v[12:13], v[42:43] op_sel_hi:[1,0]
	v_pk_mul_f32 v[10:11], v[10:11], v[42:43] op_sel_hi:[1,0]
	v_pk_mul_f32 v[8:9], v[8:9], v[42:43] op_sel_hi:[1,0]
	v_pk_mul_f32 v[6:7], v[6:7], v[42:43] op_sel_hi:[1,0]
	v_pk_mul_f32 v[4:5], v[4:5], v[42:43] op_sel_hi:[1,0]
	v_pk_mul_f32 v[2:3], v[2:3], v[42:43] op_sel_hi:[1,0]
	v_pk_mul_f32 v[0:1], v[0:1], v[42:43] op_sel_hi:[1,0]

; #define LAS __attribute__((address_space(3)))
; DI int crow(int r, int hi) { return (r & 3) + 8 * (r >> 2) + 4 * hi; }
; template <int MODE> DI void attn_unit(int b, int qb, const bf16* Qb, int qpitch, const bf16* Kb, int kpitch, const bf16* VT, bf16* O, float* ssq, ...
;     ...
;         const bool active = (k0 <= qw0 + 31) && (MODE != 0 || k0 + 63 >= qw0 - 127);
;         if (active) {
;             const LAS unsigned char* kb = lds + KOFF + buf * KSZ + r32 * PK + 16 * hi;
;             v16f p0, p1;
; #pragma unroll
;             for (int d0 = 0; d0 < ND; ++d0) {
;                 const v8s ka = *(const LAS v8s*)(kb + 32 * d0), kb2 = *(const LAS v8s*)(kb + 32 * PK + 32 * d0);
;                 if (d0 == 0) { p0 = MFMA32(ka, qr[0], (v16f){}); p1 = MFMA32(kb2, qr[0], (v16f){}); }
;                 else { p0 = MFMA32(ka, qr[d0], p0); p1 = MFMA32(kb2, qr[d0], p1); }
;             }
;             asm volatile("s_nop 15\n\ts_nop 7" : "+v"(p0), "+v"(p1));
;             if (MODE == 1) {
;                 const LAS float* fb = (const LAS float*)(lds + FOFF + buf * 256);
; #pragma unroll
;                 for (int g = 0; g < 4; ++g) {
;                     const v4f f0 = *(const LAS v4f*)(fb + 8 * g + 4 * hi), f1 = *(const LAS v4f*)(fb + 32 + 8 * g + 4 * hi);
; #pragma unroll
;                     for (int i = 0; i < 4; ++i) { p0[4 * g + i] += f0[i]; p1[4 * g + i] += f1[i]; }
;                 }
;             }
;             if (MODE == 0) {
;                 const LAS float* tb = MS + (223 - q + k0 + 4 * hi);
; #pragma unroll
;                 for (int r = 0; r < 16; ++r) { p0[r] += tb[(r & 3) + 8 * (r >> 2)]; p1[r] += tb[32 + (r & 3) + 8 * (r >> 2)]; }
;             } else if (k0 + 63 > qw0) {
; #pragma unroll
;                 for (int r = 0; r < 16; ++r) {
;                     const int kv = k0 + crow(r, hi);
;                     if (kv > q) p0[r] = NEGBIG;
;                     if (kv + 32 > q) p1[r] = NEGBIG;
;                 }
;             }
;             float rm;
;             { float ma = max3f(p0[0], p0[1], p1[0]), mb = max3f(p0[2], p0[3], p1[1]); ma = max3f(ma, p1[2], p1[3]);
; #pragma unroll
;               for (int r = 4; r < 16; r += 4) { ma = max3f(ma, p0[r], p0[r + 1]); mb = max3f(mb, p0[r + 2], p0[r + 3]); ma = max3f(ma, p1[r], p1[r + 1]); mb = max3f(mb, p1[r + 2], p1[r + 3]); }
;               rm = max2f(ma, mb); }
.LBB0_534:
	s_cmp_le_i32 s18, s27
	s_cselect_b64 s[74:75], -1, 0
	s_add_i32 s19, s18, 63
	s_cmp_ge_i32 s19, s36
	s_cselect_b64 s[84:85], -1, 0
	s_and_b64 s[74:75], s[74:75], s[84:85]
	s_andn2_b64 vcc, exec, s[74:75]
	s_cbranch_vccnz .LBB0_538
	s_mul_i32 s19, s59, 0x2400
	v_add_u32_e32 v163, s19, v199
	ds_read_b128 v[32:35], v163
	ds_read_b128 v[164:167], v163 offset:32
	ds_read_b128 v[48:51], v163 offset:4608
	s_waitcnt lgkmcnt(2)
	v_mfma_f32_32x32x16_bf16 v[32:47], v[32:35], v[66:69], 0
	s_waitcnt lgkmcnt(1)
	v_mfma_f32_32x32x16_bf16 v[32:47], v[164:167], v[70:73], v[32:47]
	ds_read_b128 v[164:167], v163 offset:4640
	s_waitcnt lgkmcnt(1)
	v_mfma_f32_32x32x16_bf16 v[48:63], v[48:51], v[66:69], 0
	s_waitcnt lgkmcnt(0)
	v_mfma_f32_32x32x16_bf16 v[48:63], v[164:167], v[70:73], v[48:63]
	ds_read_b128 v[164:167], v163 offset:64
	s_waitcnt lgkmcnt(0)
	v_mfma_f32_32x32x16_bf16 v[32:47], v[164:167], v[74:77], v[32:47]
	ds_read_b128 v[164:167], v163 offset:4672
	s_waitcnt lgkmcnt(0)
	v_mfma_f32_32x32x16_bf16 v[48:63], v[164:167], v[74:77], v[48:63]
	ds_read_b128 v[164:167], v163 offset:96
	s_waitcnt lgkmcnt(0)
	v_mfma_f32_32x32x16_bf16 v[32:47], v[164:167], v[78:81], v[32:47]
	ds_read_b128 v[164:167], v163 offset:4704
	s_waitcnt lgkmcnt(0)
	v_mfma_f32_32x32x16_bf16 v[48:63], v[164:167], v[78:81], v[48:63]
	s_nop 15
	s_nop 7
	ds_read2_b32 v[166:167], v153 offset1:1
	ds_read2_b32 v[168:169], v153 offset0:32 offset1:33
	ds_read2_b32 v[176:177], v153 offset0:2 offset1:3
	ds_read2_b32 v[178:179], v153 offset0:34 offset1:35
	ds_read2_b32 v[180:181], v153 offset0:40 offset1:41
	s_waitcnt lgkmcnt(4)
	s_nop 2
	v_add_f32_e32 v163, v166, v32
	v_add_f32_e32 v164, v33, v167
	ds_read2_b32 v[32:33], v153 offset0:8 offset1:9
	s_waitcnt lgkmcnt(4)
	v_add_f32_e32 v165, v48, v168
	v_add_f32_e32 v49, v49, v169
	s_waitcnt lgkmcnt(3)
	v_add_f32_e32 v48, v34, v176
	s_waitcnt lgkmcnt(2)
	v_add_f32_e32 v167, v50, v178
	v_add_f32_e32 v166, v35, v177
	s_waitcnt lgkmcnt(0)
	v_add_f32_e32 v50, v36, v32
	ds_read2_b32 v[34:35], v153 offset0:10 offset1:11
	ds_read2_b32 v[176:177], v153 offset0:42 offset1:43
	v_add_f32_e32 v169, v37, v33
	ds_read2_b32 v[32:33], v153 offset0:16 offset1:17
	v_add_f32_e32 v51, v51, v179
	v_add_f32_e32 v168, v53, v181
	s_waitcnt lgkmcnt(2)
	v_add_f32_e32 v53, v38, v34
	s_waitcnt lgkmcnt(1)
	v_add_f32_e32 v179, v54, v176
	ds_read2_b32 v[36:37], v153 offset0:48 offset1:49
	v_add_f32_e32 v178, v39, v35
	v_add_f32_e32 v176, v55, v177
	s_waitcnt lgkmcnt(1)
	v_add_f32_e32 v55, v40, v32
	ds_read2_b32 v[34:35], v153 offset0:18 offset1:19
	ds_read2_b32 v[38:39], v153 offset0:50 offset1:51
	v_add_f32_e32 v177, v41, v33
	ds_read2_b32 v[32:33], v153 offset0:24 offset1:25
	v_add_f32_e32 v52, v52, v180
	s_waitcnt lgkmcnt(3)
	v_add_f32_e32 v180, v56, v36
	v_add_f32_e32 v56, v57, v37
	s_waitcnt lgkmcnt(2)
	v_add_f32_e32 v54, v42, v34
	s_waitcnt lgkmcnt(0)
	v_add_f32_e32 v36, v44, v32
	v_max3_f32 v32, v163, v164, v165
	v_add_f32_e32 v40, v45, v33
	v_max3_f32 v33, v48, v166, v49
	v_max3_f32 v32, v32, v167, v51
	v_add_f32_e32 v57, v58, v38
	v_add_f32_e32 v43, v43, v35
	ds_read2_b32 v[34:35], v153 offset0:56 offset1:57
	v_add_f32_e32 v39, v59, v39
	ds_read2_b32 v[58:59], v153 offset0:26 offset1:27
	ds_read2_b32 v[182:183], v153 offset0:58 offset1:59
	v_max3_f32 v32, v32, v50, v169
	v_max3_f32 v33, v33, v53, v178
	s_waitcnt lgkmcnt(2)
	v_add_f32_e32 v38, v60, v34
	v_max3_f32 v32, v32, v52, v168
	v_max3_f32 v33, v33, v179, v176
	s_waitcnt lgkmcnt(1)
	v_add_f32_e32 v41, v46, v58
	v_max3_f32 v32, v32, v55, v177
	v_max3_f32 v33, v33, v54, v43
	v_add_f32_e32 v42, v47, v59
	v_max3_f32 v32, v32, v180, v56
	v_max3_f32 v33, v33, v57, v39
	v_add_f32_e32 v34, v61, v35
	v_max3_f32 v32, v32, v36, v40
	v_max3_f32 v33, v33, v41, v42
	s_waitcnt lgkmcnt(0)
	v_add_f32_e32 v37, v62, v182
	v_add_f32_e32 v35, v63, v183
	v_max3_f32 v32, v32, v38, v34
	v_max3_f32 v33, v33, v37, v35
	v_max_f32_e32 v32, v32, v33
	v_mov_b32_e32 v33, v32
	s_nop 1
	v_permlane32_swap_b32_e32 v32, v33
	v_max_f32_e32 v32, v32, v33
	v_max_f32_e32 v33, v157, v32
	v_sub_f32_e32 v32, v157, v33
	v_exp_f32_e32 v32, v32
	s_nop 0
	v_cmp_neq_f32_e32 vcc, 1.0, v32
	s_cbranch_vccz .LBB0_537
	v_pk_mul_f32 v[14:15], v[14:15], v[32:33] op_sel_hi:[1,0]
	v_pk_mul_f32 v[12:13], v[12:13], v[32:33] op_sel_hi:[1,0]
	v_pk_mul_f32 v[10:11], v[10:11], v[32:33] op_sel_hi:[1,0]
	v_pk_mul_f32 v[8:9], v[8:9], v[32:33] op_sel_hi:[1,0]
	v_pk_mul_f32 v[6:7], v[6:7], v[32:33] op_sel_hi:[1,0]
	v_pk_mul_f32 v[4:5], v[4:5], v[32:33] op_sel_hi:[1,0]
	v_pk_mul_f32 v[2:3], v[2:3], v[32:33] op_sel_hi:[1,0]
	v_pk_mul_f32 v[0:1], v[0:1], v[32:33] op_sel_hi:[1,0]
	v_pk_mul_f32 v[30:31], v[30:31], v[32:33] op_sel_hi:[1,0]
	v_pk_mul_f32 v[28:29], v[28:29], v[32:33] op_sel_hi:[1,0]
	v_pk_mul_f32 v[26:27], v[26:27], v[32:33] op_sel_hi:[1,0]
	v_pk_mul_f32 v[24:25], v[24:25], v[32:33] op_sel_hi:[1,0]
	v_pk_mul_f32 v[22:23], v[22:23], v[32:33] op_sel_hi:[1,0]
	v_pk_mul_f32 v[20:21], v[20:21], v[32:33] op_sel_hi:[1,0]
	v_pk_mul_f32 v[18:19], v[18:19], v[32:33] op_sel_hi:[1,0]
	v_pk_mul_f32 v[16:17], v[16:17], v[32:33] op_sel_hi:[1,0]
